# global attention row sums with v_pk_add_f32 (15 packed + 2 scalar per tile instead of 32 scalar adds)
# baseline (speedup 1.0000x reference)
; DI void attn_item(const Params& p, int layer, int item, char* smem) {
;     ...
;   const int qpos = qpos0 + wid * 32 + l32;
;   bf16x8 qf[4];
; #pragma unroll
;   for (int s = 0; s < 4; ++s) qf[s] = *(const bf16x8*)(Qb + (size_t)qpos * 64 + s * 16 + h * 8);
;   f32x16 o0, o1;
; #pragma unroll
;   for (int r = 0; r < 16; ++r) { o0[r] = 0.f; o1[r] = 0.f; }
;   const int btype = (mode == 3) ? (hh < 6 ? 0 : (hh < 10 ? 1 : 2)) : (mode == 0 ? 2 : (mode == 1 ? 1 : 0));
;   float m_fix = p.bounds[layer * 8 + btype];
;   if (mode == 1) m_fix += p.bounds[layer * 8 + 4 + hh];
;   f32x16 cinit, lacc;
; #pragma unroll
;   for (int r = 0; r < 16; ++r) { cinit[r] = -m_fix; lacc[r] = 0.f; }
;   const bf16x8 ones = {(short)0x3F80, (short)0x3F80, (short)0x3F80, (short)0x3F80, (short)0x3F80, (short)0x3F80, (short)0x3F80, (short)0x3F80};
;   const int lr = tid >> 3, lc = tid & 7;
;   uint4 ka0, va0, kb0, vb0;
;     ...
;       const char* sK = smem + bufsel * KV_B;
;       const char* sV = sK + KT_B;
;       f32x16 S[2];
; #pragma unroll
;       for (int kt = 0; kt < 2; ++kt) {
; #pragma unroll
;         for (int s = 0; s < 4; ++s) {
;           bf16x8 kf = *(const bf16x8*)(sK + (kt * 32 + l32) * KROW + s * 32 + h * 16);
;           S[kt] = MFMA32(kf, qf[s], s == 0 ? cinit : S[kt]);
;         }
;       }
;       if (tile < 64 && maskmode == 1) {
;         int qr = tq >> 6, qc = tq & 63;
;         int ws = min(max(qc - 8, 0), 48);
;         int dr = tile - qr + 7;
; #pragma unroll
;         for (int kt = 0; kt < 2; ++kt)
; #pragma unroll
;           for (int r = 0; r < 16; ++r) {
;             int kc = kt * 32 + crow(r, h);
;             bool ok = (unsigned)(kc - ws) < 16u;
;             int bi = ok ? (dr * 31 + kc - qc + 15) : 0;
;             float bv = s_rpb[bi];
;             S[kt][r] = ok ? (S[kt][r] + bv) : -INFINITY;
;           }
;       } else if (tile < 64 && maskmode == 2) {
; #pragma unroll
;         for (int kt = 0; kt < 2; ++kt)
; #pragma unroll
;           for (int r = 0; r < 16; ++r) {
;             int tk = tile * 64 + kt * 32 + crow(r, h);
;             int dd = tq - tk;
;             bool ok = (dd <= 128) && (dd >= -128);
;             S[kt][r] = ok ? S[kt][r] : -INFINITY;
;           }
;       }
; #pragma unroll
;       for (int r = 0; r < 16; ++r) {
;         S[0][r] = __builtin_amdgcn_exp2f(S[0][r]);
;         S[1][r] = __builtin_amdgcn_exp2f(S[1][r]);
;       }
.LBB0_259:
	s_mul_hi_i32 s0, s14, 0x2aaaaaab
	s_lshr_b32 s1, s0, 31
	s_ashr_i32 s5, s0, 4
	s_add_i32 s5, s5, s1
	s_mul_i32 s0, s5, 0x60
	s_sub_i32 s0, s14, s0
	v_mov_b32_e32 v32, v213
	s_ashr_i32 s4, s0, 4
	s_lshl_b32 s0, s0, 8
	s_and_b32 s8, s0, 0xf00
	s_lshl_b32 s0, s5, 5
	v_ashrrev_i32_e32 v0, 1, v32
	s_add_i32 s1, s4, s0
	s_mul_i32 s2, s4, 0x56
	v_and_b32_e32 v0, 0xffffffe0, v0
	v_and_b32_e32 v36, 31, v32
	s_bfe_u32 s3, s2, 0x1000f
	s_bfe_u32 s2, s2, 0x80008
	s_add_i32 s1, s1, 22
	v_add_u32_e32 v0, s8, v0
	s_add_i32 s2, s2, s3
	s_mul_hi_i32 s3, s1, 0x88000
	s_mul_i32 s1, s1, 0x88000
	v_or_b32_e32 v134, v0, v36
	s_add_u32 s6, s88, s1
	v_ashrrev_i32_e32 v135, 31, v134
	v_bfe_u32 v140, v32, 5, 1
	s_addc_u32 s7, s89, s3
	v_lshlrev_b64 v[2:3], 7, v[134:135]
	v_lshl_add_u64 v[2:3], s[6:7], 0, v[2:3]
	v_lshlrev_b32_e32 v18, 4, v140
	v_mov_b32_e32 v19, v1
	v_readlane_b32 s6, v254, 50
	v_lshl_add_u64 v[2:3], v[2:3], 0, v[18:19]
	v_readlane_b32 s7, v254, 51
	global_load_dwordx4 v[98:101], v[2:3], off
	global_load_dwordx4 v[102:105], v[2:3], off offset:32
	global_load_dwordx4 v[106:109], v[2:3], off offset:64
	global_load_dwordx4 v[110:113], v[2:3], off offset:96
	s_sext_i32_i8 s2, s2
	global_load_dword v0, v1, s[6:7] offset:8
	s_add_i32 s2, s0, s2
	s_mul_i32 s3, s2, 0x88000
	s_add_i32 s0, s2, 28
	s_mul_hi_i32 s1, s0, 0x88000
	s_add_i32 s0, s3, 0xee0000
	v_ashrrev_i32_e32 v30, 3, v32
	s_add_u32 s0, s88, s0
	v_ashrrev_i32_e32 v31, 31, v30
	s_addc_u32 s1, s89, s1
	v_lshlrev_b32_e32 v19, 4, v32
	v_lshlrev_b64 v[20:21], 7, v[30:31]
	v_lshl_add_u64 v[136:137], s[0:1], 0, v[20:21]
	s_mov_b32 s6, 0x80000
	s_add_i32 s2, s2, 30
	s_add_i32 s3, s3, 0xff0000
	s_mul_hi_i32 s9, s2, 0x88000
	s_add_u32 s2, s88, s3
	s_addc_u32 s3, s89, s9
	v_mov_b64_e32 v[26:27], s[2:3]
	v_mad_i64_i32 v[138:139], s[2:3], v30, s28, v[26:27]
	s_movk_i32 s3, 0x90
	s_mov_b32 s2, 0x82000
	v_mul_lo_u32 v30, v30, s3
	v_add_u32_e32 v30, 16, v30
	v_add_u32_e32 v144, 16, v18
	v_mul_u32_u24_e32 v145, 0x90, v36
	v_mad_u32_u24 v146, v36, s3, v144
	s_waitcnt vmcnt(0)
	v_xor_b32_e32 v2, 0x80000000, v0
	v_and_b32_e32 v0, 0x70, v19
	v_lshl_add_u64 v[34:35], v[136:137], 0, v[0:1]
	v_add_co_u32_e32 v22, vcc, s6, v34
	v_add_u32_e32 v135, v30, v0
	s_nop 0
	v_addc_co_u32_e32 v23, vcc, 0, v35, vcc
	global_load_dwordx4 v[22:25], v[22:23], off
	v_add_co_u32_e32 v26, vcc, s2, v34
	v_lshl_add_u64 v[74:75], v[138:139], 0, v[0:1]
	s_nop 0
	v_addc_co_u32_e32 v27, vcc, 0, v35, vcc
	global_load_dwordx4 v[26:29], v[26:27], off
	s_movk_i32 s2, 0x2000
	v_mov_b32_e32 v3, v2
	v_mov_b32_e32 v4, v2
	v_mov_b32_e32 v5, v2
	v_mov_b32_e32 v6, v2
	v_mov_b32_e32 v7, v2
	v_mov_b32_e32 v8, v2
	v_mov_b32_e32 v9, v2
	v_mov_b32_e32 v10, v2
	v_mov_b32_e32 v11, v2
	v_mov_b32_e32 v12, v2
	v_mov_b32_e32 v13, v2
	v_mov_b32_e32 v14, v2
	v_mov_b32_e32 v15, v2
	v_mov_b32_e32 v16, v2
	v_mov_b32_e32 v17, v2
	s_waitcnt vmcnt(0)
	ds_write_b128 v135, v[22:25]
	v_lshlrev_b32_e32 v22, 3, v32
	v_and_b32_e32 v22, 8, v22
	v_and_or_b32 v19, v19, s74, v22
	v_add_co_u32_e32 v22, vcc, s2, v74
	v_add_u32_e32 v19, v30, v19
	s_nop 0
	v_addc_co_u32_e32 v23, vcc, 0, v75, vcc
	global_load_dwordx4 v[30:33], v[22:23], off
	s_mov_b32 s2, 0x84000
	v_add_co_u32_e32 v24, vcc, s2, v34
	v_add_u32_e32 v141, 0x2000, v19
	s_nop 0
	v_addc_co_u32_e32 v25, vcc, 0, v35, vcc
	global_load_dwordx4 v[66:69], v[24:25], off
	v_lshl_add_u64 v[24:25], s[0:1], 0, v[0:1]
	v_lshl_add_u64 v[76:77], v[24:25], 0, v[20:21]
	s_mov_b32 s0, 0x86000
	v_add_u32_e32 v143, 0x6800, v19
	s_waitcnt vmcnt(0)
	ds_write2_b64 v141, v[30:31], v[32:33] offset0:128 offset1:130
	v_mad_u32_u24 v30, v36, s3, 16
	v_add_u32_e32 v142, v30, v18
	global_load_dwordx4 v[70:73], v[22:23], off offset:256
	global_load_dwordx4 v[30:33], v[22:23], off offset:128
	v_add_co_u32_e32 v18, vcc, s0, v76
	s_waitcnt lgkmcnt(0)
	s_barrier
	ds_write_b128 v135, v[26:29] offset:18432
	v_addc_co_u32_e32 v19, vcc, 0, v77, vcc
	s_waitcnt vmcnt(0)
	ds_write2_b64 v143, v[30:31], v[32:33] offset0:128 offset1:130
	global_load_dwordx4 v[114:117], v[18:19], off
	global_load_dwordx4 v[118:121], v[22:23], off offset:384
	ds_read_b128 v[34:37], v146
	ds_read_b128 v[38:41], v146 offset:32
	v_mov_b64_e32 v[132:133], s[94:95]
	v_mov_b64_e32 v[130:131], s[92:93]
	s_waitcnt lgkmcnt(1)
	v_mfma_f32_32x32x16_bf16 v[18:33], v[34:37], v[98:101], v[2:17]
	ds_read_b128 v[34:37], v146 offset:64
	ds_read_b128 v[50:53], v146 offset:4608
	s_waitcnt lgkmcnt(2)
	v_mfma_f32_32x32x16_bf16 v[18:33], v[38:41], v[102:105], v[18:33]
	s_waitcnt lgkmcnt(1)
	v_mfma_f32_32x32x16_bf16 v[18:33], v[34:37], v[106:109], v[18:33]
	ds_read_b128 v[34:37], v146 offset:96
	s_waitcnt lgkmcnt(0)
	v_mfma_f32_32x32x16_bf16 v[18:33], v[34:37], v[110:113], v[18:33]
	v_mfma_f32_32x32x16_bf16 v[34:49], v[50:53], v[98:101], v[2:17]
	ds_read_b128 v[50:53], v146 offset:4640
	s_nop 9
	v_exp_f32_e32 v18, v18
	v_exp_f32_e32 v19, v19
	v_exp_f32_e32 v20, v20
	v_exp_f32_e32 v21, v21
	v_exp_f32_e32 v22, v22
	v_exp_f32_e32 v23, v23
	s_waitcnt lgkmcnt(0)
	v_mfma_f32_32x32x16_bf16 v[34:49], v[50:53], v[102:105], v[34:49]
	ds_read_b128 v[50:53], v146 offset:4672
	v_exp_f32_e32 v24, v24
	v_exp_f32_e32 v25, v25
	v_cvt_pk_bf16_f32 v18, v18, v19
	v_cvt_pk_bf16_f32 v19, v20, v21
	v_cvt_pk_bf16_f32 v20, v22, v23
	v_cvt_pk_bf16_f32 v21, v24, v25
	s_waitcnt lgkmcnt(0)
	v_mfma_f32_32x32x16_bf16 v[34:49], v[50:53], v[106:109], v[34:49]
	ds_read_b128 v[50:53], v146 offset:4704
	ds_read_b128 v[22:25], v142 offset:9216
	ds_read_b128 v[78:81], v142 offset:9248
	v_exp_f32_e32 v82, v26
	v_exp_f32_e32 v83, v27
	v_exp_f32_e32 v84, v28
	v_exp_f32_e32 v85, v29
	v_exp_f32_e32 v122, v30
	s_waitcnt lgkmcnt(2)
; DI void attn_item(const Params& p, int layer, int item, char* smem) {
;     ...
;       f32x16 S[2];
; #pragma unroll
;       for (int kt = 0; kt < 2; ++kt) {
; #pragma unroll
;         for (int s = 0; s < 4; ++s) {
;           bf16x8 kf = *(const bf16x8*)(sK + (kt * 32 + l32) * KROW + s * 32 + h * 16);
;           S[kt] = MFMA32(kf, qf[s], s == 0 ? cinit : S[kt]);
;         }
;       }
;       if (tile < 64 && maskmode == 1) {
;         int qr = tq >> 6, qc = tq & 63;
;         int ws = min(max(qc - 8, 0), 48);
;         int dr = tile - qr + 7;
; #pragma unroll
;         for (int kt = 0; kt < 2; ++kt)
; #pragma unroll
;           for (int r = 0; r < 16; ++r) {
;             int kc = kt * 32 + crow(r, h);
;             bool ok = (unsigned)(kc - ws) < 16u;
;             int bi = ok ? (dr * 31 + kc - qc + 15) : 0;
;             float bv = s_rpb[bi];
;             S[kt][r] = ok ? (S[kt][r] + bv) : -INFINITY;
;           }
;       } else if (tile < 64 && maskmode == 2) {
; #pragma unroll
;         for (int kt = 0; kt < 2; ++kt)
; #pragma unroll
;           for (int r = 0; r < 16; ++r) {
;             int tk = tile * 64 + kt * 32 + crow(r, h);
;             int dd = tq - tk;
;             bool ok = (dd <= 128) && (dd >= -128);
;             S[kt][r] = ok ? S[kt][r] : -INFINITY;
;           }
;       }
; #pragma unroll
;       for (int r = 0; r < 16; ++r) {
;         S[0][r] = __builtin_amdgcn_exp2f(S[0][r]);
;         S[1][r] = __builtin_amdgcn_exp2f(S[1][r]);
;       }
; #pragma unroll
;       for (int kt = 0; kt < 2; ++kt)
; #pragma unroll
;         for (int s2 = 0; s2 < 2; ++s2) {
;           uint4 pw;
;           pw.x = pack_bf16(S[kt][8 * s2 + 0], S[kt][8 * s2 + 1]);
;           pw.y = pack_bf16(S[kt][8 * s2 + 2], S[kt][8 * s2 + 3]);
;           pw.z = pack_bf16(S[kt][8 * s2 + 4], S[kt][8 * s2 + 5]);
;           pw.w = pack_bf16(S[kt][8 * s2 + 6], S[kt][8 * s2 + 7]);
;           bf16x8 pf = __builtin_bit_cast(bf16x8, pw);
;           const int koff = (kt * 32 + 16 * s2 + 8 * h) * 2;
;           {
;             bf16x8 vf = *(const bf16x8*)(sV + l32 * VROW + koff);
;             o0 = MFMA32(vf, pf, o0);
;             lacc = MFMA32(ones, pf, lacc);
;           }
;           {
;             bf16x8 vf = *(const bf16x8*)(sV + (32 + l32) * VROW + koff);
;             o1 = MFMA32(vf, pf, o1);
;           }
;         }
;     ...
;   for (int it = 0; it < n_it; it += 2) {
	v_mfma_f32_32x32x16_bf16 v[34:49], v[50:53], v[110:113], v[34:49]
	v_exp_f32_e32 v124, v31
	v_exp_f32_e32 v126, v32
	v_exp_f32_e32 v128, v33
	v_cvt_pk_bf16_f32 v82, v82, v83
	v_cvt_pk_bf16_f32 v83, v84, v85
	v_cvt_pk_bf16_f32 v84, v122, v124
	v_cvt_pk_bf16_f32 v85, v126, v128
	s_nop 4
	v_exp_f32_e32 v86, v34
	v_exp_f32_e32 v87, v35
	v_exp_f32_e32 v88, v36
	v_exp_f32_e32 v89, v37
	v_exp_f32_e32 v90, v38
	v_exp_f32_e32 v91, v39
	v_exp_f32_e32 v92, v40
	v_exp_f32_e32 v93, v41
	v_exp_f32_e32 v94, v42
	v_exp_f32_e32 v95, v43
	v_exp_f32_e32 v96, v44
	v_exp_f32_e32 v97, v45
	v_exp_f32_e32 v123, v46
	v_exp_f32_e32 v125, v47
	v_exp_f32_e32 v127, v48
	v_exp_f32_e32 v129, v49
	s_waitcnt lgkmcnt(1)
	v_mfma_f32_32x32x16_bf16 v[34:49], v[22:25], v[18:21], 0
	ds_read_b128 v[22:25], v142 offset:13824
	s_waitcnt lgkmcnt(1)
	v_mfma_f32_32x32x16_bf16 v[34:49], v[78:81], v[82:85], v[34:49]
	ds_read_b128 v[78:81], v142 offset:13856
	v_mfma_f32_32x32x16_bf16 v[50:65], v[130:133], v[18:21], 0
	s_waitcnt lgkmcnt(1)
	v_mfma_f32_32x32x16_bf16 v[18:33], v[22:25], v[18:21], 0
	v_mfma_f32_32x32x16_bf16 v[50:65], v[130:133], v[82:85], v[50:65]
	s_waitcnt lgkmcnt(0)
	v_mfma_f32_32x32x16_bf16 v[18:33], v[78:81], v[82:85], v[18:33]
	ds_read_b128 v[82:85], v142 offset:9280
	v_cvt_pk_bf16_f32 v78, v86, v87
	v_cvt_pk_bf16_f32 v79, v88, v89
	v_cvt_pk_bf16_f32 v80, v90, v91
	v_cvt_pk_bf16_f32 v81, v92, v93
	s_waitcnt lgkmcnt(0)
	s_nop 0
	v_mfma_f32_32x32x16_bf16 v[34:49], v[82:85], v[78:81], v[34:49]
	ds_read_b128 v[82:85], v142 offset:13888
	s_waitcnt lgkmcnt(0)
	v_mfma_f32_32x32x16_bf16 v[18:33], v[82:85], v[78:81], v[18:33]
	ds_read_b128 v[82:85], v142 offset:9312
	v_mfma_f32_32x32x16_bf16 v[50:65], v[130:133], v[78:81], v[50:65]
	v_cvt_pk_bf16_f32 v78, v94, v95
	v_cvt_pk_bf16_f32 v79, v96, v97
	v_cvt_pk_bf16_f32 v80, v123, v125
	v_cvt_pk_bf16_f32 v81, v127, v129
	s_waitcnt lgkmcnt(0)
	s_nop 0
	v_mfma_f32_32x32x16_bf16 v[34:49], v[82:85], v[78:81], v[34:49]
	ds_read_b128 v[82:85], v142 offset:13920
	s_waitcnt lgkmcnt(0)
	s_barrier
	ds_write_b128 v135, v[66:69]
	ds_write2_b64 v141, v[70:71], v[72:73] offset0:128 offset1:130
	global_load_dwordx4 v[122:125], v[76:77], off
	global_load_dwordx4 v[126:129], v[74:75], off
	v_mfma_f32_32x32x16_bf16 v[50:65], v[130:133], v[78:81], v[50:65]
	v_mfma_f32_32x32x16_bf16 v[18:33], v[82:85], v[78:81], v[18:33]
	ds_read_b128 v[82:85], v146 offset:18432
	ds_read_b128 v[86:89], v146 offset:18464
	s_mov_b32 s2, 2
	v_add_u32_e32 v144, v144, v145
	s_waitcnt lgkmcnt(1)
	v_mfma_f32_32x32x16_bf16 v[66:81], v[82:85], v[98:101], v[2:17]
	ds_read_b128 v[82:85], v146 offset:18496
	ds_read_b128 v[148:151], v146 offset:23040
	s_waitcnt lgkmcnt(2)
	v_mfma_f32_32x32x16_bf16 v[66:81], v[86:89], v[102:105], v[66:81]
	s_waitcnt lgkmcnt(1)
	v_mfma_f32_32x32x16_bf16 v[66:81], v[82:85], v[106:109], v[66:81]
	ds_read_b128 v[82:85], v146 offset:18528
	s_waitcnt lgkmcnt(0)
	v_mfma_f32_32x32x16_bf16 v[66:81], v[82:85], v[110:113], v[66:81]
	v_mfma_f32_32x32x16_bf16 v[82:97], v[148:151], v[98:101], v[2:17]
	ds_read_b128 v[148:151], v146 offset:23072
	s_nop 9
	v_exp_f32_e32 v66, v66
	v_exp_f32_e32 v67, v67
	v_exp_f32_e32 v68, v68
	v_exp_f32_e32 v69, v69
	v_exp_f32_e32 v70, v70
	v_exp_f32_e32 v71, v71
	s_waitcnt lgkmcnt(0)
	v_mfma_f32_32x32x16_bf16 v[82:97], v[148:151], v[102:105], v[82:97]
	ds_read_b128 v[148:151], v146 offset:23104
	v_exp_f32_e32 v72, v72
	v_exp_f32_e32 v73, v73
	v_cvt_pk_bf16_f32 v66, v66, v67
	v_cvt_pk_bf16_f32 v67, v68, v69
	v_cvt_pk_bf16_f32 v68, v70, v71
	v_cvt_pk_bf16_f32 v69, v72, v73
	s_waitcnt lgkmcnt(0)
	v_mfma_f32_32x32x16_bf16 v[82:97], v[148:151], v[106:109], v[82:97]
	ds_read_b128 v[146:149], v146 offset:23136
	v_exp_f32_e32 v78, v78
	v_exp_f32_e32 v79, v79
	v_exp_f32_e32 v80, v80
	v_exp_f32_e32 v81, v81
	s_waitcnt lgkmcnt(0)
	v_mfma_f32_32x32x16_bf16 v[82:97], v[146:149], v[110:113], v[82:97]
	v_exp_f32_e32 v146, v74
	v_exp_f32_e32 v147, v75
	v_exp_f32_e32 v148, v76
	v_exp_f32_e32 v149, v77
	ds_read_b128 v[70:73], v142 offset:27648
	ds_read_b128 v[74:77], v142 offset:27680
	s_nop 5
	v_exp_f32_e32 v82, v82
	s_waitcnt lgkmcnt(1)
	v_mfma_f32_32x32x16_bf16 v[34:49], v[70:73], v[66:69], v[34:49]
	ds_read_b128 v[70:73], v142 offset:32256
	v_exp_f32_e32 v83, v83
	v_exp_f32_e32 v84, v84
	v_exp_f32_e32 v85, v85
	v_exp_f32_e32 v86, v86
	v_exp_f32_e32 v87, v87
	v_exp_f32_e32 v88, v88
	s_waitcnt lgkmcnt(0)
	v_mfma_f32_32x32x16_bf16 v[18:33], v[70:73], v[66:69], v[18:33]
	ds_read_b128 v[70:73], v142 offset:32288
	v_exp_f32_e32 v89, v89
	v_exp_f32_e32 v90, v90
	v_exp_f32_e32 v91, v91
	v_exp_f32_e32 v92, v92
	v_exp_f32_e32 v93, v93
	v_exp_f32_e32 v94, v94
	v_mfma_f32_32x32x16_bf16 v[50:65], v[130:133], v[66:69], v[50:65]
	v_cvt_pk_bf16_f32 v66, v146, v147
	v_cvt_pk_bf16_f32 v67, v148, v149
	v_cvt_pk_bf16_f32 v68, v78, v79
	v_cvt_pk_bf16_f32 v69, v80, v81
	v_exp_f32_e32 v95, v95
	v_exp_f32_e32 v96, v96
	v_exp_f32_e32 v97, v97
	s_waitcnt lgkmcnt(0)
	v_mfma_f32_32x32x16_bf16 v[18:33], v[70:73], v[66:69], v[18:33]
	ds_read_b128 v[70:73], v142 offset:27712
	v_mfma_f32_32x32x16_bf16 v[34:49], v[74:77], v[66:69], v[34:49]
	v_mfma_f32_32x32x16_bf16 v[50:65], v[130:133], v[66:69], v[50:65]
	v_cvt_pk_bf16_f32 v66, v82, v83
	v_cvt_pk_bf16_f32 v67, v84, v85
	v_cvt_pk_bf16_f32 v68, v86, v87
	v_cvt_pk_bf16_f32 v69, v88, v89
	s_waitcnt lgkmcnt(0)
	s_nop 0
	v_mfma_f32_32x32x16_bf16 v[34:49], v[70:73], v[66:69], v[34:49]
	ds_read_b128 v[70:73], v142 offset:32320
	s_waitcnt lgkmcnt(0)
	v_mfma_f32_32x32x16_bf16 v[18:33], v[70:73], v[66:69], v[18:33]
	ds_read_b128 v[70:73], v142 offset:27744
	v_mfma_f32_32x32x16_bf16 v[50:65], v[130:133], v[66:69], v[50:65]
	v_cvt_pk_bf16_f32 v66, v90, v91
	v_cvt_pk_bf16_f32 v67, v92, v93
	v_cvt_pk_bf16_f32 v68, v94, v95
	v_cvt_pk_bf16_f32 v69, v96, v97
	s_waitcnt lgkmcnt(0)
	s_nop 0
	v_mfma_f32_32x32x16_bf16 v[34:49], v[70:73], v[66:69], v[34:49]
	ds_read_b128 v[70:73], v142 offset:32352
	s_waitcnt lgkmcnt(0)
	s_barrier
	v_mfma_f32_32x32x16_bf16 v[50:65], v[130:133], v[66:69], v[50:65]
	v_mfma_f32_32x32x16_bf16 v[18:33], v[70:73], v[66:69], v[18:33]
	s_nop 11
	v_mov_b32_e32 v52, 0
	v_mov_b32_e32 v53, 0
	v_mov_b32_e32 v54, 0
	v_mov_b32_e32 v55, 0
	v_mov_b32_e32 v56, 0
	s_branch .LBB0_261
; DI void attn_item(const Params& p, int layer, int item, char* smem) {
;     ...
;       f32x16 S[2];
; #pragma unroll
;       for (int kt = 0; kt < 2; ++kt) {
; #pragma unroll
;         for (int s = 0; s < 4; ++s) {
;           bf16x8 kf = *(const bf16x8*)(sK + (kt * 32 + l32) * KROW + s * 32 + h * 16);
;           S[kt] = MFMA32(kf, qf[s], s == 0 ? cinit : S[kt]);
;         }
;       }
;       if (tile < 64 && maskmode == 1) {
;         int qr = tq >> 6, qc = tq & 63;
;         int ws = min(max(qc - 8, 0), 48);
;         int dr = tile - qr + 7;
; #pragma unroll
;         for (int kt = 0; kt < 2; ++kt)
; #pragma unroll
;           for (int r = 0; r < 16; ++r) {
;             int kc = kt * 32 + crow(r, h);
;             bool ok = (unsigned)(kc - ws) < 16u;
;             int bi = ok ? (dr * 31 + kc - qc + 15) : 0;
;             float bv = s_rpb[bi];
;             S[kt][r] = ok ? (S[kt][r] + bv) : -INFINITY;
;           }
;       } else if (tile < 64 && maskmode == 2) {
; #pragma unroll
;         for (int kt = 0; kt < 2; ++kt)
; #pragma unroll
;           for (int r = 0; r < 16; ++r) {
;             int tk = tile * 64 + kt * 32 + crow(r, h);
;             int dd = tq - tk;
;             bool ok = (dd <= 128) && (dd >= -128);
;             S[kt][r] = ok ? S[kt][r] : -INFINITY;
;           }
;       }
; #pragma unroll
;       for (int r = 0; r < 16; ++r) {
;         S[0][r] = __builtin_amdgcn_exp2f(S[0][r]);
;         S[1][r] = __builtin_amdgcn_exp2f(S[1][r]);
;       }
; #pragma unroll
;       for (int kt = 0; kt < 2; ++kt)
; #pragma unroll
;         for (int s2 = 0; s2 < 2; ++s2) {
;           uint4 pw;
;           pw.x = pack_bf16(S[kt][8 * s2 + 0], S[kt][8 * s2 + 1]);
;           pw.y = pack_bf16(S[kt][8 * s2 + 2], S[kt][8 * s2 + 3]);
;           pw.z = pack_bf16(S[kt][8 * s2 + 4], S[kt][8 * s2 + 5]);
;           pw.w = pack_bf16(S[kt][8 * s2 + 6], S[kt][8 * s2 + 7]);
;           bf16x8 pf = __builtin_bit_cast(bf16x8, pw);
;           const int koff = (kt * 32 + 16 * s2 + 8 * h) * 2;
;           {
;             bf16x8 vf = *(const bf16x8*)(sV + l32 * VROW + koff);
;             o0 = MFMA32(vf, pf, o0);
;             lacc = MFMA32(ones, pf, lacc);
;           }
;           {
;             bf16x8 vf = *(const bf16x8*)(sV + (32 + l32) * VROW + koff);
;             o1 = MFMA32(vf, pf, o1);
;           }
;         }
.LBB0_260:
	ds_read_b128 v[82:85], v144 offset:18432
	ds_read_b128 v[86:89], v144 offset:18464
	s_mov_b64 s[6:7], 0x100
	s_add_i32 s2, s2, 2
	v_lshl_add_u64 v[138:139], v[138:139], 0, s[6:7]
	s_waitcnt lgkmcnt(1)
	v_mfma_f32_32x32x16_bf16 v[66:81], v[82:85], v[98:101], v[2:17]
	ds_read_b128 v[82:85], v144 offset:18496
	ds_read_b128 v[130:133], v144 offset:23040
	v_lshl_add_u64 v[136:137], v[136:137], 0, s[96:97]
	s_andn2_b64 vcc, exec, s[0:1]
	s_waitcnt lgkmcnt(2)
	v_mfma_f32_32x32x16_bf16 v[66:81], v[86:89], v[102:105], v[66:81]
	s_waitcnt lgkmcnt(1)
	v_mfma_f32_32x32x16_bf16 v[66:81], v[82:85], v[106:109], v[66:81]
	ds_read_b128 v[82:85], v144 offset:18528
	s_waitcnt lgkmcnt(0)
	v_mfma_f32_32x32x16_bf16 v[66:81], v[82:85], v[110:113], v[66:81]
	v_mfma_f32_32x32x16_bf16 v[82:97], v[130:133], v[98:101], v[2:17]
	ds_read_b128 v[130:133], v144 offset:23072
	s_nop 9
	v_exp_f32_e32 v66, v66
	v_exp_f32_e32 v67, v67
	v_exp_f32_e32 v68, v68
	v_exp_f32_e32 v69, v69
	v_exp_f32_e32 v70, v70
	v_exp_f32_e32 v71, v71
	s_waitcnt lgkmcnt(0)
	v_mfma_f32_32x32x16_bf16 v[82:97], v[130:133], v[102:105], v[82:97]
	ds_read_b128 v[130:133], v144 offset:23104
	v_exp_f32_e32 v72, v72
	v_exp_f32_e32 v73, v73
	v_pk_add_f32 v[52:53], v[52:53], v[66:67]
	v_pk_add_f32 v[54:55], v[54:55], v[68:69]
	v_cvt_pk_bf16_f32 v66, v66, v67
	v_cvt_pk_bf16_f32 v67, v68, v69
	s_waitcnt lgkmcnt(0)
	v_mfma_f32_32x32x16_bf16 v[82:97], v[130:133], v[106:109], v[82:97]
	ds_read_b128 v[130:133], v144 offset:23136
	v_pk_add_f32 v[52:53], v[52:53], v[70:71]
	v_cvt_pk_bf16_f32 v68, v70, v71
	v_pk_add_f32 v[54:55], v[54:55], v[72:73]
	v_cvt_pk_bf16_f32 v69, v72, v73
	v_exp_f32_e32 v145, v78
	v_exp_f32_e32 v146, v79
	s_waitcnt lgkmcnt(0)
	v_mfma_f32_32x32x16_bf16 v[82:97], v[130:133], v[110:113], v[82:97]
	v_exp_f32_e32 v147, v80
	v_exp_f32_e32 v148, v81
	v_exp_f32_e32 v130, v74
	v_exp_f32_e32 v131, v75
	v_exp_f32_e32 v132, v76
	v_exp_f32_e32 v133, v77
	ds_read_b128 v[70:73], v142 offset:27648
	ds_read_b128 v[74:77], v142 offset:27680
	ds_read_b128 v[78:81], v142 offset:32256
	v_add_f32_e32 v56, v56, v145
	v_pk_add_f32 v[52:53], v[52:53], v[146:147]
	v_add_f32_e32 v56, v56, v148
	v_exp_f32_e32 v82, v82
	s_waitcnt lgkmcnt(2)
	v_mfma_f32_32x32x16_bf16 v[34:49], v[70:73], v[66:69], v[34:49]
	v_exp_f32_e32 v83, v83
	v_exp_f32_e32 v84, v84
	v_exp_f32_e32 v85, v85
	v_pk_add_f32 v[54:55], v[54:55], v[130:131]
	v_pk_add_f32 v[52:53], v[52:53], v[132:133]
	v_exp_f32_e32 v86, v86
	v_exp_f32_e32 v87, v87
	v_exp_f32_e32 v88, v88
	v_exp_f32_e32 v89, v89
	s_waitcnt lgkmcnt(0)
	v_mfma_f32_32x32x16_bf16 v[18:33], v[78:81], v[66:69], v[18:33]
	v_cvt_pk_bf16_f32 v66, v130, v131
	v_cvt_pk_bf16_f32 v67, v132, v133
	v_cvt_pk_bf16_f32 v68, v145, v146
	v_cvt_pk_bf16_f32 v69, v147, v148
	v_exp_f32_e32 v90, v90
	v_exp_f32_e32 v91, v91
	v_exp_f32_e32 v92, v92
	v_mfma_f32_32x32x16_bf16 v[34:49], v[74:77], v[66:69], v[34:49]
	ds_read_b128 v[74:77], v142 offset:32288
	v_exp_f32_e32 v93, v93
	v_exp_f32_e32 v94, v94
	v_exp_f32_e32 v95, v95
	v_exp_f32_e32 v96, v96
	v_exp_f32_e32 v97, v97
	v_pk_add_f32 v[54:55], v[54:55], v[82:83]
	s_waitcnt lgkmcnt(0)
	v_mfma_f32_32x32x16_bf16 v[18:33], v[74:77], v[66:69], v[18:33]
	ds_read_b128 v[74:77], v142 offset:27712
	v_pk_add_f32 v[52:53], v[52:53], v[84:85]
	v_pk_add_f32 v[54:55], v[54:55], v[86:87]
	v_cvt_pk_bf16_f32 v66, v82, v83
	v_cvt_pk_bf16_f32 v67, v84, v85
	v_cvt_pk_bf16_f32 v68, v86, v87
	v_cvt_pk_bf16_f32 v69, v88, v89
	s_waitcnt lgkmcnt(0)
	s_nop 0
	v_mfma_f32_32x32x16_bf16 v[34:49], v[74:77], v[66:69], v[34:49]
	ds_read_b128 v[74:77], v142 offset:32320
	v_pk_add_f32 v[52:53], v[52:53], v[88:89]
	v_pk_add_f32 v[54:55], v[54:55], v[90:91]
	s_waitcnt lgkmcnt(0)
	v_mfma_f32_32x32x16_bf16 v[18:33], v[74:77], v[66:69], v[18:33]
	v_cvt_pk_bf16_f32 v66, v90, v91
	v_cvt_pk_bf16_f32 v67, v92, v93
	v_cvt_pk_bf16_f32 v68, v94, v95
	v_cvt_pk_bf16_f32 v69, v96, v97
	ds_read_b128 v[74:77], v142 offset:27744
	ds_read_b128 v[70:73], v142 offset:32352
	v_pk_add_f32 v[52:53], v[52:53], v[92:93]
	v_pk_add_f32 v[54:55], v[54:55], v[94:95]
	v_pk_add_f32 v[52:53], v[52:53], v[96:97]
	s_waitcnt lgkmcnt(0)
	s_barrier
	v_mfma_f32_32x32x16_bf16 v[34:49], v[74:77], v[66:69], v[34:49]
	v_mfma_f32_32x32x16_bf16 v[18:33], v[70:73], v[66:69], v[18:33]
	s_cbranch_vccz .LBB0_267

; DI void attn_item(const Params& p, int layer, int item, char* smem) {
;     ...
;       f32x16 S[2];
; #pragma unroll
;       for (int kt = 0; kt < 2; ++kt) {
; #pragma unroll
;         for (int s = 0; s < 4; ++s) {
;           bf16x8 kf = *(const bf16x8*)(sK + (kt * 32 + l32) * KROW + s * 32 + h * 16);
;           S[kt] = MFMA32(kf, qf[s], s == 0 ? cinit : S[kt]);
;         }
;       }
;       if (tile < 64 && maskmode == 1) {
;         int qr = tq >> 6, qc = tq & 63;
;         int ws = min(max(qc - 8, 0), 48);
;         int dr = tile - qr + 7;
; #pragma unroll
;         for (int kt = 0; kt < 2; ++kt)
; #pragma unroll
;           for (int r = 0; r < 16; ++r) {
;             int kc = kt * 32 + crow(r, h);
;             bool ok = (unsigned)(kc - ws) < 16u;
;             int bi = ok ? (dr * 31 + kc - qc + 15) : 0;
;             float bv = s_rpb[bi];
;             S[kt][r] = ok ? (S[kt][r] + bv) : -INFINITY;
;           }
;       } else if (tile < 64 && maskmode == 2) {
; #pragma unroll
;         for (int kt = 0; kt < 2; ++kt)
; #pragma unroll
;           for (int r = 0; r < 16; ++r) {
;             int tk = tile * 64 + kt * 32 + crow(r, h);
;             int dd = tq - tk;
;             bool ok = (dd <= 128) && (dd >= -128);
;             S[kt][r] = ok ? S[kt][r] : -INFINITY;
;           }
;       }
; #pragma unroll
;       for (int r = 0; r < 16; ++r) {
;         S[0][r] = __builtin_amdgcn_exp2f(S[0][r]);
;         S[1][r] = __builtin_amdgcn_exp2f(S[1][r]);
;       }
; #pragma unroll
;       for (int kt = 0; kt < 2; ++kt)
; #pragma unroll
;         for (int s2 = 0; s2 < 2; ++s2) {
;           uint4 pw;
;           pw.x = pack_bf16(S[kt][8 * s2 + 0], S[kt][8 * s2 + 1]);
;           pw.y = pack_bf16(S[kt][8 * s2 + 2], S[kt][8 * s2 + 3]);
;           pw.z = pack_bf16(S[kt][8 * s2 + 4], S[kt][8 * s2 + 5]);
;           pw.w = pack_bf16(S[kt][8 * s2 + 6], S[kt][8 * s2 + 7]);
;           bf16x8 pf = __builtin_bit_cast(bf16x8, pw);
;           const int koff = (kt * 32 + 16 * s2 + 8 * h) * 2;
;           {
;             bf16x8 vf = *(const bf16x8*)(sV + l32 * VROW + koff);
;             o0 = MFMA32(vf, pf, o0);
;             lacc = MFMA32(ones, pf, lacc);
;           }
;           {
;             bf16x8 vf = *(const bf16x8*)(sV + (32 + l32) * VROW + koff);
;             o1 = MFMA32(vf, pf, o1);
;           }
;         }
;     ...
;   for (int it = 0; it < n_it; it += 2) {
.LBB0_263:
	ds_read_b128 v[82:85], v144
	ds_read_b128 v[86:89], v144 offset:32
	s_cmpk_gt_u32 s2, 0x41
	s_cselect_b64 s[0:1], -1, 0
	s_and_b64 vcc, exec, s[0:1]
	s_waitcnt lgkmcnt(1)
	v_mfma_f32_32x32x16_bf16 v[66:81], v[82:85], v[98:101], v[2:17]
	ds_read_b128 v[82:85], v144 offset:64
	ds_read_b128 v[146:149], v144 offset:4608
	s_waitcnt lgkmcnt(2)
	v_mfma_f32_32x32x16_bf16 v[66:81], v[86:89], v[102:105], v[66:81]
	s_waitcnt lgkmcnt(1)
	v_mfma_f32_32x32x16_bf16 v[66:81], v[82:85], v[106:109], v[66:81]
	ds_read_b128 v[82:85], v144 offset:96
	s_waitcnt lgkmcnt(0)
	v_mfma_f32_32x32x16_bf16 v[66:81], v[82:85], v[110:113], v[66:81]
	v_mfma_f32_32x32x16_bf16 v[82:97], v[146:149], v[98:101], v[2:17]
	ds_read_b128 v[146:149], v144 offset:4640
	s_nop 9
	v_exp_f32_e32 v66, v66
	v_exp_f32_e32 v67, v67
	v_exp_f32_e32 v68, v68
	v_exp_f32_e32 v69, v69
	v_exp_f32_e32 v70, v70
	v_exp_f32_e32 v71, v71
	s_waitcnt lgkmcnt(0)
	v_mfma_f32_32x32x16_bf16 v[82:97], v[146:149], v[102:105], v[82:97]
	ds_read_b128 v[146:149], v144 offset:4672
	v_exp_f32_e32 v72, v72
	v_exp_f32_e32 v73, v73
	v_exp_f32_e32 v145, v74
	v_pk_add_f32 v[54:55], v[54:55], v[66:67]
	v_pk_add_f32 v[52:53], v[52:53], v[68:69]
	v_cvt_pk_bf16_f32 v66, v66, v67
	v_cvt_pk_bf16_f32 v67, v68, v69
	s_waitcnt lgkmcnt(0)
	v_mfma_f32_32x32x16_bf16 v[82:97], v[146:149], v[106:109], v[82:97]
	ds_read_b128 v[146:149], v144 offset:4704
	v_pk_add_f32 v[54:55], v[54:55], v[70:71]
	v_cvt_pk_bf16_f32 v68, v70, v71
	v_pk_add_f32 v[52:53], v[52:53], v[72:73]
	v_cvt_pk_bf16_f32 v69, v72, v73
	v_exp_f32_e32 v150, v79
	v_exp_f32_e32 v151, v80
	s_waitcnt lgkmcnt(0)
	v_mfma_f32_32x32x16_bf16 v[82:97], v[146:149], v[110:113], v[82:97]
	v_exp_f32_e32 v152, v81
	v_exp_f32_e32 v146, v75
	v_exp_f32_e32 v147, v76
	v_exp_f32_e32 v148, v77
	v_exp_f32_e32 v149, v78
	ds_read_b128 v[70:73], v142 offset:9216
	ds_read_b128 v[74:77], v142 offset:9248
	ds_read_b128 v[78:81], v142 offset:13824
	v_add_f32_e32 v56, v56, v145
	v_pk_add_f32 v[54:55], v[54:55], v[150:151]
	v_add_f32_e32 v56, v56, v152
	v_exp_f32_e32 v82, v82
	s_waitcnt lgkmcnt(2)
	v_mfma_f32_32x32x16_bf16 v[34:49], v[70:73], v[66:69], v[34:49]
	v_exp_f32_e32 v83, v83
	v_exp_f32_e32 v84, v84
	v_exp_f32_e32 v85, v85
	v_pk_add_f32 v[52:53], v[52:53], v[146:147]
	v_pk_add_f32 v[54:55], v[54:55], v[148:149]
	v_exp_f32_e32 v86, v86
	v_exp_f32_e32 v87, v87
	v_exp_f32_e32 v88, v88
	v_exp_f32_e32 v89, v89
	s_waitcnt lgkmcnt(0)
	v_mfma_f32_32x32x16_bf16 v[18:33], v[78:81], v[66:69], v[18:33]
	v_cvt_pk_bf16_f32 v66, v145, v146
	v_cvt_pk_bf16_f32 v67, v147, v148
	v_cvt_pk_bf16_f32 v68, v149, v150
	v_cvt_pk_bf16_f32 v69, v151, v152
	v_exp_f32_e32 v90, v90
	v_exp_f32_e32 v91, v91
	v_exp_f32_e32 v92, v92
	v_mfma_f32_32x32x16_bf16 v[34:49], v[74:77], v[66:69], v[34:49]
	ds_read_b128 v[74:77], v142 offset:13856
	v_exp_f32_e32 v93, v93
	v_exp_f32_e32 v94, v94
	v_exp_f32_e32 v95, v95
	v_exp_f32_e32 v96, v96
	v_exp_f32_e32 v97, v97
	v_pk_add_f32 v[52:53], v[52:53], v[82:83]
	s_waitcnt lgkmcnt(0)
	v_mfma_f32_32x32x16_bf16 v[18:33], v[74:77], v[66:69], v[18:33]
	ds_read_b128 v[74:77], v142 offset:9280
	v_pk_add_f32 v[54:55], v[54:55], v[84:85]
	v_pk_add_f32 v[52:53], v[52:53], v[86:87]
	v_cvt_pk_bf16_f32 v66, v82, v83
	v_cvt_pk_bf16_f32 v67, v84, v85
	v_cvt_pk_bf16_f32 v68, v86, v87
	v_cvt_pk_bf16_f32 v69, v88, v89
	s_waitcnt lgkmcnt(0)
	s_nop 0
	v_mfma_f32_32x32x16_bf16 v[34:49], v[74:77], v[66:69], v[34:49]
	ds_read_b128 v[74:77], v142 offset:13888
	v_pk_add_f32 v[54:55], v[54:55], v[88:89]
	v_pk_add_f32 v[52:53], v[52:53], v[90:91]
	s_waitcnt lgkmcnt(0)
	v_mfma_f32_32x32x16_bf16 v[18:33], v[74:77], v[66:69], v[18:33]
	v_cvt_pk_bf16_f32 v66, v90, v91
	v_cvt_pk_bf16_f32 v67, v92, v93
	v_cvt_pk_bf16_f32 v68, v94, v95
	v_cvt_pk_bf16_f32 v69, v96, v97
	ds_read_b128 v[74:77], v142 offset:9312
	ds_read_b128 v[70:73], v142 offset:13920
	v_pk_add_f32 v[54:55], v[54:55], v[92:93]
	v_pk_add_f32 v[52:53], v[52:53], v[94:95]
	v_pk_add_f32 v[54:55], v[54:55], v[96:97]
	s_waitcnt lgkmcnt(0)
	s_barrier
	v_mfma_f32_32x32x16_bf16 v[34:49], v[74:77], v[66:69], v[34:49]
	v_mfma_f32_32x32x16_bf16 v[18:33], v[70:73], v[66:69], v[18:33]
	s_cbranch_vccnz .LBB0_265
	s_waitcnt vmcnt(1)
	ds_write_b128 v135, v[122:125]
	s_waitcnt vmcnt(0)
	ds_write2_b64 v141, v[126:127], v[128:129] offset0:128 offset1:130

; DI void attn_item(const Params& p, int layer, int item, char* smem) {
;     ...
;   float l_tot = lacc[0];
;   if (hasSink) l_tot += __builtin_amdgcn_exp2f(sinkv * LOG2E - m_fix);
;   float inv = 1.f / l_tot;
;   int T = (mode == 3) ? (TLAT + b * 256 + (qpos - 4096)) : (b * 4096 + qpos);
;   u16* od = p.O + (size_t)T * LDK + head16 * 64;
; #pragma unroll
;   for (int g = 0; g < 4; ++g) {
;     int d0 = 8 * g + 4 * h;
;     *(uint2*)(od + d0) = make_uint2(pack_bf16(o0[4 * g] * inv, o0[4 * g + 1] * inv), pack_bf16(o0[4 * g + 2] * inv, o0[4 * g + 3] * inv));
;     *(uint2*)(od + 32 + d0) = make_uint2(pack_bf16(o1[4 * g] * inv, o1[4 * g + 1] * inv), pack_bf16(o1[4 * g + 2] * inv, o1[4 * g + 3] * inv));
;   }
.LBB0_267:
	s_nop 5
	v_add_f32_e32 v52, v52, v53
	v_add_f32_e32 v54, v54, v55
	v_add_f32_e32 v52, v52, v56
	v_add_f32_e32 v51, v52, v54
	v_mov_b32_e32 v52, 0
	s_nop 0
	v_mov_b32_e32 v52, v51
	s_nop 1
	v_permlane32_swap_b32_e32 v51, v52
	s_nop 1
	v_add_f32_e32 v50, v50, v51
	v_add_f32_e32 v50, v50, v52
	v_div_scale_f32 v0, s[0:1], v50, v50, 1.0
	v_rcp_f32_e32 v3, v0
	v_lshl_add_u32 v2, s5, 12, v134
	s_lshl_b32 s0, s4, 6
	s_ashr_i32 s1, s0, 31
	v_fma_f32 v4, -v0, v3, 1.0
	v_fmac_f32_e32 v3, v4, v3
	v_div_scale_f32 v4, vcc, 1.0, v50, 1.0
	v_mul_f32_e32 v5, v4, v3
	v_fma_f32 v6, -v0, v5, v4
	v_fmac_f32_e32 v5, v6, v3
	v_fma_f32 v0, -v0, v5, v4
	v_div_fmas_f32 v0, v0, v3, v5
	v_ashrrev_i32_e32 v3, 31, v2
	v_lshlrev_b64 v[2:3], 11, v[2:3]
	v_div_fixup_f32 v4, v0, v50, 1.0
	v_lshl_add_u64 v[2:3], s[90:91], 0, v[2:3]
	v_lshl_add_u64 v[2:3], s[0:1], 1, v[2:3]
	v_pk_mul_f32 v[6:7], v[34:35], v[4:5] op_sel_hi:[1,0]
	v_pk_mul_f32 v[8:9], v[36:37], v[4:5] op_sel_hi:[1,0]
	v_lshlrev_b32_e32 v0, 3, v140
	v_cvt_pk_bf16_f32 v6, v6, v7
	v_cvt_pk_bf16_f32 v7, v8, v9
	v_lshl_add_u64 v[2:3], v[2:3], 0, v[0:1]
	global_store_dwordx2 v[2:3], v[6:7], off offset:1280
	v_pk_mul_f32 v[6:7], v[4:5], v[18:19] op_sel_hi:[0,1]
	v_pk_mul_f32 v[8:9], v[4:5], v[20:21] op_sel_hi:[0,1]
	v_cvt_pk_bf16_f32 v6, v6, v7
	v_cvt_pk_bf16_f32 v7, v8, v9
	global_store_dwordx2 v[2:3], v[6:7], off offset:1344
	v_pk_mul_f32 v[6:7], v[38:39], v[4:5] op_sel_hi:[1,0]
	v_pk_mul_f32 v[8:9], v[40:41], v[4:5] op_sel_hi:[1,0]
	v_cvt_pk_bf16_f32 v6, v6, v7
	v_cvt_pk_bf16_f32 v7, v8, v9
	global_store_dwordx2 v[2:3], v[6:7], off offset:1296
	v_pk_mul_f32 v[6:7], v[4:5], v[22:23] op_sel_hi:[0,1]
	v_pk_mul_f32 v[8:9], v[4:5], v[24:25] op_sel_hi:[0,1]
	v_cvt_pk_bf16_f32 v6, v6, v7
	v_cvt_pk_bf16_f32 v7, v8, v9
	global_store_dwordx2 v[2:3], v[6:7], off offset:1360
	v_pk_mul_f32 v[6:7], v[42:43], v[4:5] op_sel_hi:[1,0]
	v_pk_mul_f32 v[8:9], v[44:45], v[4:5] op_sel_hi:[1,0]
	v_cvt_pk_bf16_f32 v6, v6, v7
	v_cvt_pk_bf16_f32 v7, v8, v9
	global_store_dwordx2 v[2:3], v[6:7], off offset:1312
	v_pk_mul_f32 v[6:7], v[4:5], v[26:27] op_sel_hi:[0,1]
	v_pk_mul_f32 v[8:9], v[4:5], v[28:29] op_sel_hi:[0,1]
	v_cvt_pk_bf16_f32 v6, v6, v7
	v_cvt_pk_bf16_f32 v7, v8, v9
	global_store_dwordx2 v[2:3], v[6:7], off offset:1376
	v_pk_mul_f32 v[6:7], v[46:47], v[4:5] op_sel_hi:[1,0]
	v_pk_mul_f32 v[8:9], v[48:49], v[4:5] op_sel_hi:[1,0]
	v_cvt_pk_bf16_f32 v6, v6, v7
	v_cvt_pk_bf16_f32 v7, v8, v9
	global_store_dwordx2 v[2:3], v[6:7], off offset:1328
	v_pk_mul_f32 v[6:7], v[4:5], v[30:31] op_sel_hi:[0,1]
	v_pk_mul_f32 v[4:5], v[4:5], v[32:33] op_sel_hi:[0,1]
	v_cvt_pk_bf16_f32 v6, v6, v7
	v_cvt_pk_bf16_f32 v7, v4, v5
	global_store_dwordx2 v[2:3], v[6:7], off offset:1392
	s_and_saveexec_b64 s[0:1], s[68:69]
	s_cbranch_execz .LBB0_236
	s_branch .LBB0_498
